# w_in (QKV) K loop also merged into 4 phases (p6 addresses updated in place, p8 temporary moved off the B fragment registers); 7 of 8 GEMM K loops merged
# baseline (speedup 1.0000x reference)
; #define PG8_STAGE(bufoff, gbase, voff) do { _Pragma("unroll") for (int _i = 0; _i < 2; ++_i) \
;     __builtin_amdgcn_global_load_lds((const unsigned*)((const char*)(gbase) + (voff)[_i]), (LAS unsigned*)(lds + (bufoff) + ldsw + _i * 8192), 16, 0, 0); } while (0)
; #define PG8_LDA(dst, b, h) do { _Pragma("unroll") for (int m = 0; m < 4; ++m) _Pragma("unroll") for (int k = 0; k < 2; ++k) dst[m][k] = *(const LAS bf16x8*)(lds + PG8_SA(b, h) + aoff + m * 2048 + k * 1024); } while (0)
; #define PG8_LDB(dst, b, h) do { _Pragma("unroll") for (int n = 0; n < 2; ++n) _Pragma("unroll") for (int k = 0; k < 2; ++k) dst[n][k] = *(const LAS bf16x8*)(lds + PG8_SB(b, h) + boff + n * 2048 + k * 1024); } while (0)
; #define PG8_MMA(ai, bj, At, Bt) do { __builtin_amdgcn_s_setprio(1); _Pragma("unroll") for (int m = 0; m < 4; ++m) _Pragma("unroll") for (int n = 0; n < 2; ++n) _Pragma("unroll") for (int k = 0; k < 2; ++k) \
;     acc[ai][bj][m][n] = __builtin_amdgcn_mfma_f32_16x16x32_bf16(Bt[n][k], At[m][k], acc[ai][bj][m][n], 0, 0, 0); __builtin_amdgcn_s_setprio(0); } while (0)
; #define PG8_WAIT_L(n) asm volatile("s_waitcnt lgkmcnt(" #n ")" ::: "memory")
; #define PG8_BAR __builtin_amdgcn_s_barrier()
; #define PG8_SCHED __builtin_amdgcn_sched_barrier(0)
; template <class Epi, class Sched>
; DI void gemm_phase(LAS unsigned char* lds, const Gemm g, const Sched& S, const Epi& E) {
;     ...
;     for (int t = 0; t < nt; t += 2) {
;       const bool last = (t == nt - 2);
;       const char* a1 = cA + (size_t)(t + 1) * kstep;
;       const char* a2 = last ? nA : cA + (size_t)(t + 2) * kstep; const char* b2 = last ? nB : cB + (size_t)(t + 2) * kstep;
;       const char* a3 = a2 + kstep; const char* b3 = b2 + kstep;
;       PG8_LDB(B0, 0, 0); PG8_SCHED; PG8_LDA(At, 0, 0); PG8_STAGE(PG8_SA(1, 1), a1 + hstep, voffA);
;       PG8_WAIT_L(8); PG8_BAR; PG8_WAIT_L(0); PG8_MMA(0, 0, At, B0); PG8_BAR; PG8_SCHED;
;       PG8_LDB(B1, 0, 1); PG8_STAGE(PG8_SB(0, 0), b2, voffB);
;       PG8_BAR; PG8_WAIT_L(0); PG8_MMA(0, 1, At, B1); PG8_BAR;
;       PG8_LDA(At, 0, 1); PG8_STAGE(PG8_SA(0, 0), a2, voffA);
;       PG8_BAR; PG8_WAIT_L(0); PG8_MMA(1, 0, At, B0); PG8_BAR; PG8_SCHED;
;       PG8_STAGE(PG8_SB(0, 1), b2 + hstepB, voffB);
.LBB0_519:
	s_add_i32 s23, s6, 2
	s_add_u32 s8, s2, 0x80
	s_addc_u32 s7, s3, 0
	s_add_i32 s24, 16, 0x10000
	v_add_u32_e32 v0, s24, v215
	ds_read_b128 v[66:69], v0
	ds_read_b128 v[70:73], v0 offset:1024
	ds_read_b128 v[74:77], v0 offset:2048
	ds_read_b128 v[78:81], v0 offset:3072
	s_cmp_eq_u32 s41, s6
	s_cselect_b32 s6, s0, s8
	s_cselect_b32 s7, s1, s7
	s_cselect_b32 s9, s21, s22
	s_cselect_b32 s8, s20, s11
	v_lshl_add_u64 v[206:207], s[2:3], 0, v[202:203]
	s_add_i32 m0, s30, 0xc000
	ds_read_b128 v[82:85], v216
	ds_read_b128 v[86:89], v216 offset:1024
	ds_read_b128 v[94:97], v216 offset:2048
	ds_read_b128 v[98:101], v216 offset:3072
	ds_read_b128 v[114:117], v216 offset:4096
	ds_read_b128 v[118:121], v216 offset:5120
	ds_read_b128 v[122:125], v216 offset:6144
	ds_read_b128 v[126:129], v216 offset:7168
	global_load_lds_dwordx4 v[206:207], off
	v_lshl_add_u64 v[206:207], s[2:3], 0, v[204:205]
	s_add_i32 m0, s30, 0xe000
	s_nop 0
	global_load_lds_dwordx4 v[206:207], off
	s_add_i32 s25, 16, 0x14000
	s_add_i32 s24, s24, s29
	v_add_u32_e32 v0, s25, v215
	ds_read_b128 v[206:209], v0
	ds_read_b128 v[218:221], v0 offset:1024
	ds_read_b128 v[222:225], v0 offset:2048
	ds_read_b128 v[226:229], v0 offset:3072
	s_waitcnt lgkmcnt(0)
	s_barrier
	v_mfma_f32_16x16x32_bf16 v[174:177], v[66:69], v[82:85], v[174:177]
	v_mfma_f32_16x16x32_bf16 v[170:173], v[74:77], v[82:85], v[170:173]
	v_mfma_f32_16x16x32_bf16 v[158:161], v[66:69], v[94:97], v[158:161]
	v_mfma_f32_16x16x32_bf16 v[154:157], v[74:77], v[94:97], v[154:157]
	v_mfma_f32_16x16x32_bf16 v[142:145], v[66:69], v[114:117], v[142:145]
	v_mfma_f32_16x16x32_bf16 v[138:141], v[74:77], v[114:117], v[138:141]
	v_mfma_f32_16x16x32_bf16 v[110:113], v[66:69], v[122:125], v[110:113]
	v_mfma_f32_16x16x32_bf16 v[106:109], v[74:77], v[122:125], v[106:109]
	v_mfma_f32_16x16x32_bf16 v[174:177], v[70:73], v[86:89], v[174:177]
	v_mfma_f32_16x16x32_bf16 v[170:173], v[78:81], v[86:89], v[170:173]
	v_mfma_f32_16x16x32_bf16 v[158:161], v[70:73], v[98:101], v[158:161]
	v_mfma_f32_16x16x32_bf16 v[154:157], v[78:81], v[98:101], v[154:157]
	v_mfma_f32_16x16x32_bf16 v[142:145], v[70:73], v[118:121], v[142:145]
	v_mfma_f32_16x16x32_bf16 v[138:141], v[78:81], v[118:121], v[138:141]
	v_mfma_f32_16x16x32_bf16 v[110:113], v[70:73], v[126:129], v[110:113]
	v_mfma_f32_16x16x32_bf16 v[106:109], v[78:81], v[126:129], v[106:109]
	v_mfma_f32_16x16x32_bf16 v[166:169], v[206:209], v[82:85], v[166:169]
	v_mfma_f32_16x16x32_bf16 v[82:85], v[222:225], v[82:85], v[162:165]
	v_mfma_f32_16x16x32_bf16 v[166:169], v[218:221], v[86:89], v[166:169]
	v_mfma_f32_16x16x32_bf16 v[82:85], v[226:229], v[86:89], v[82:85]
	v_mfma_f32_16x16x32_bf16 v[86:89], v[206:209], v[94:97], v[150:153]
	v_mfma_f32_16x16x32_bf16 v[94:97], v[222:225], v[94:97], v[146:149]
	v_mfma_f32_16x16x32_bf16 v[102:105], v[206:209], v[122:125], v[102:105]
	v_mfma_f32_16x16x32_bf16 v[90:93], v[222:225], v[122:125], v[90:93]
	v_mfma_f32_16x16x32_bf16 v[86:89], v[218:221], v[98:101], v[86:89]
	v_mfma_f32_16x16x32_bf16 v[94:97], v[226:229], v[98:101], v[94:97]
	v_mfma_f32_16x16x32_bf16 v[98:101], v[206:209], v[114:117], v[134:137]
	v_mfma_f32_16x16x32_bf16 v[114:117], v[222:225], v[114:117], v[130:133]
	v_mfma_f32_16x16x32_bf16 v[102:105], v[218:221], v[126:129], v[102:105]
	v_mfma_f32_16x16x32_bf16 v[90:93], v[226:229], v[126:129], v[90:93]
	v_mfma_f32_16x16x32_bf16 v[98:101], v[218:221], v[118:121], v[98:101]
	v_mfma_f32_16x16x32_bf16 v[114:117], v[226:229], v[118:121], v[114:117]
	s_mov_b32 m0, s30
	v_lshl_add_u64 v[250:251], s[6:7], 0, v[192:193]
	s_barrier
	ds_read_b128 v[118:121], v216 offset:16384
	ds_read_b128 v[122:125], v216 offset:17408
	ds_read_b128 v[126:129], v216 offset:18432
	ds_read_b128 v[130:133], v216 offset:19456
	ds_read_b128 v[134:137], v216 offset:20480
	ds_read_b128 v[146:149], v216 offset:21504
	ds_read_b128 v[150:153], v216 offset:22528
	ds_read_b128 v[162:165], v216 offset:23552
	global_load_lds_dwordx4 v[250:251], off
	v_lshl_add_u64 v[180:181], s[6:7], 0, v[188:189]
	s_mov_b32 m0, s31
	s_nop 0
	global_load_lds_dwordx4 v[180:181], off
	v_lshl_add_u64 v[246:247], s[8:9], 0, v[190:191]
	s_mov_b32 m0, s24
	s_nop 0
	global_load_lds_dwordx4 v[246:247], off
	v_lshl_add_u64 v[248:249], s[8:9], 0, v[186:187]
	s_add_i32 m0, s24, 0x2000
	s_nop 0
	global_load_lds_dwordx4 v[248:249], off
	s_add_u32 s8, s8, s14
	s_addc_u32 s9, s9, s15
	s_add_i32 s24, s25, s29
	v_lshl_add_u64 v[182:183], s[8:9], 0, v[190:191]
	s_mov_b32 m0, s24
	v_lshl_add_u64 v[184:185], s[8:9], 0, v[186:187]
	global_load_lds_dwordx4 v[182:183], off
	s_add_i32 m0, s24, 0x2000
	s_nop 0
	global_load_lds_dwordx4 v[184:185], off
	s_waitcnt vmcnt(6)
	s_waitcnt lgkmcnt(0)
	s_barrier
; #define PG8_STAGE(bufoff, gbase, voff) do { _Pragma("unroll") for (int _i = 0; _i < 2; ++_i) \
;     __builtin_amdgcn_global_load_lds((const unsigned*)((const char*)(gbase) + (voff)[_i]), (LAS unsigned*)(lds + (bufoff) + ldsw + _i * 8192), 16, 0, 0); } while (0)
; #define PG8_LDA(dst, b, h) do { _Pragma("unroll") for (int m = 0; m < 4; ++m) _Pragma("unroll") for (int k = 0; k < 2; ++k) dst[m][k] = *(const LAS bf16x8*)(lds + PG8_SA(b, h) + aoff + m * 2048 + k * 1024); } while (0)
; #define PG8_LDB(dst, b, h) do { _Pragma("unroll") for (int n = 0; n < 2; ++n) _Pragma("unroll") for (int k = 0; k < 2; ++k) dst[n][k] = *(const LAS bf16x8*)(lds + PG8_SB(b, h) + boff + n * 2048 + k * 1024); } while (0)
; #define PG8_MMA(ai, bj, At, Bt) do { __builtin_amdgcn_s_setprio(1); _Pragma("unroll") for (int m = 0; m < 4; ++m) _Pragma("unroll") for (int n = 0; n < 2; ++n) _Pragma("unroll") for (int k = 0; k < 2; ++k) \
;     acc[ai][bj][m][n] = __builtin_amdgcn_mfma_f32_16x16x32_bf16(Bt[n][k], At[m][k], acc[ai][bj][m][n], 0, 0, 0); __builtin_amdgcn_s_setprio(0); } while (0)
; #define PG8_WAIT_V(n) asm volatile("s_waitcnt vmcnt(" #n ")" ::: "memory")
; #define PG8_WAIT_L(n) asm volatile("s_waitcnt lgkmcnt(" #n ")" ::: "memory")
; #define PG8_BAR __builtin_amdgcn_s_barrier()
; #define PG8_SCHED __builtin_amdgcn_sched_barrier(0)
; template <class Epi, class Sched>
; DI void gemm_phase(LAS unsigned char* lds, const Gemm g, const Sched& S, const Epi& E) {
;     ...
;       PG8_BAR; PG8_WAIT_L(0); PG8_MMA(1, 0, At, B0); PG8_BAR; PG8_SCHED;
;       PG8_STAGE(PG8_SB(0, 1), b2 + hstepB, voffB);
;       PG8_WAIT_V(6); PG8_BAR; PG8_MMA(1, 1, At, B1); PG8_BAR;
;       PG8_LDB(B0, 1, 0); PG8_SCHED; PG8_LDA(At, 1, 0); PG8_STAGE(PG8_SA(0, 1), a2 + hstep, voffA);
;       PG8_WAIT_L(8); PG8_BAR; PG8_WAIT_L(0); PG8_MMA(0, 0, At, B0); PG8_BAR; PG8_SCHED;
;       PG8_LDB(B1, 1, 1); PG8_STAGE(PG8_SB(1, 0), b3, voffB);
;       PG8_BAR; PG8_WAIT_L(0); PG8_MMA(0, 1, At, B1); PG8_BAR;
	v_mfma_f32_16x16x32_bf16 v[62:65], v[66:69], v[118:121], v[62:65]
	v_mfma_f32_16x16x32_bf16 v[58:61], v[74:77], v[118:121], v[58:61]
	v_mfma_f32_16x16x32_bf16 v[46:49], v[66:69], v[126:129], v[46:49]
	v_mfma_f32_16x16x32_bf16 v[42:45], v[74:77], v[126:129], v[42:45]
	v_mfma_f32_16x16x32_bf16 v[30:33], v[66:69], v[134:137], v[30:33]
	v_mfma_f32_16x16x32_bf16 v[26:29], v[74:77], v[134:137], v[26:29]
	v_mfma_f32_16x16x32_bf16 v[14:17], v[66:69], v[150:153], v[14:17]
	v_mfma_f32_16x16x32_bf16 v[10:13], v[74:77], v[150:153], v[10:13]
	v_mfma_f32_16x16x32_bf16 v[62:65], v[70:73], v[122:125], v[62:65]
	v_mfma_f32_16x16x32_bf16 v[58:61], v[78:81], v[122:125], v[58:61]
	v_mfma_f32_16x16x32_bf16 v[46:49], v[70:73], v[130:133], v[46:49]
	v_mfma_f32_16x16x32_bf16 v[42:45], v[78:81], v[130:133], v[42:45]
	v_mfma_f32_16x16x32_bf16 v[30:33], v[70:73], v[146:149], v[30:33]
	v_mfma_f32_16x16x32_bf16 v[26:29], v[78:81], v[146:149], v[26:29]
	v_mfma_f32_16x16x32_bf16 v[14:17], v[70:73], v[162:165], v[14:17]
	v_mfma_f32_16x16x32_bf16 v[10:13], v[78:81], v[162:165], v[10:13]
	v_mfma_f32_16x16x32_bf16 v[54:57], v[206:209], v[118:121], v[54:57]
	v_mfma_f32_16x16x32_bf16 v[50:53], v[222:225], v[118:121], v[50:53]
	v_mfma_f32_16x16x32_bf16 v[38:41], v[206:209], v[126:129], v[38:41]
	v_mfma_f32_16x16x32_bf16 v[34:37], v[222:225], v[126:129], v[34:37]
	v_mfma_f32_16x16x32_bf16 v[22:25], v[206:209], v[134:137], v[22:25]
	v_mfma_f32_16x16x32_bf16 v[18:21], v[222:225], v[134:137], v[18:21]
	v_mfma_f32_16x16x32_bf16 v[6:9], v[206:209], v[150:153], v[6:9]
	v_mfma_f32_16x16x32_bf16 v[2:5], v[222:225], v[150:153], v[2:5]
	v_mfma_f32_16x16x32_bf16 v[54:57], v[218:221], v[122:125], v[54:57]
	v_mfma_f32_16x16x32_bf16 v[50:53], v[226:229], v[122:125], v[50:53]
	v_mfma_f32_16x16x32_bf16 v[38:41], v[218:221], v[130:133], v[38:41]
	v_mfma_f32_16x16x32_bf16 v[34:37], v[226:229], v[130:133], v[34:37]
	v_mfma_f32_16x16x32_bf16 v[22:25], v[218:221], v[146:149], v[22:25]
	v_mfma_f32_16x16x32_bf16 v[18:21], v[226:229], v[146:149], v[18:21]
	v_mfma_f32_16x16x32_bf16 v[6:9], v[218:221], v[162:165], v[6:9]
	v_mfma_f32_16x16x32_bf16 v[2:5], v[226:229], v[162:165], v[2:5]
	s_add_i32 s8, 16, 0x18000
	v_add_u32_e32 v0, s8, v215
	s_barrier
	ds_read_b128 v[66:69], v0
	ds_read_b128 v[70:73], v0 offset:1024
	ds_read_b128 v[74:77], v0 offset:2048
	ds_read_b128 v[78:81], v0 offset:3072
	s_add_u32 s6, s6, s12
	s_addc_u32 s7, s7, s13
	s_mov_b32 m0, s34
	v_lshl_add_u64 v[134:135], s[6:7], 0, v[192:193]
	ds_read_b128 v[118:121], v216 offset:32768
	ds_read_b128 v[122:125], v216 offset:33792
	ds_read_b128 v[126:129], v216 offset:34816
	ds_read_b128 v[130:133], v216 offset:35840
	ds_read_b128 v[206:209], v216 offset:36864
	ds_read_b128 v[218:221], v216 offset:37888
	ds_read_b128 v[222:225], v216 offset:38912
	ds_read_b128 v[226:229], v216 offset:39936
	global_load_lds_dwordx4 v[134:135], off
	v_lshl_add_u64 v[134:135], s[6:7], 0, v[188:189]
	s_mov_b32 m0, s35
	s_nop 0
	global_load_lds_dwordx4 v[134:135], off
	s_add_i32 s6, 16, 0x1c000
	s_add_i32 s7, s8, s29
	v_add_u32_e32 v0, s6, v215
	ds_read_b128 v[230:233], v0
	ds_read_b128 v[234:237], v0 offset:1024
	ds_read_b128 v[238:241], v0 offset:2048
	ds_read_b128 v[242:245], v0 offset:3072
	s_waitcnt lgkmcnt(0)
	s_barrier
	v_mfma_f32_16x16x32_bf16 v[134:137], v[66:69], v[118:121], v[174:177]
	v_mfma_f32_16x16x32_bf16 v[174:177], v[70:73], v[122:125], v[134:137]
	v_mfma_f32_16x16x32_bf16 v[134:137], v[74:77], v[118:121], v[170:173]
	v_mfma_f32_16x16x32_bf16 v[170:173], v[78:81], v[122:125], v[134:137]
	v_mfma_f32_16x16x32_bf16 v[134:137], v[66:69], v[126:129], v[158:161]
	v_mfma_f32_16x16x32_bf16 v[158:161], v[70:73], v[130:133], v[134:137]
	v_mfma_f32_16x16x32_bf16 v[134:137], v[74:77], v[126:129], v[154:157]
	v_mfma_f32_16x16x32_bf16 v[154:157], v[78:81], v[130:133], v[134:137]
	v_mfma_f32_16x16x32_bf16 v[134:137], v[66:69], v[206:209], v[142:145]
	v_mfma_f32_16x16x32_bf16 v[142:145], v[70:73], v[218:221], v[134:137]
	v_mfma_f32_16x16x32_bf16 v[134:137], v[74:77], v[206:209], v[138:141]
	v_mfma_f32_16x16x32_bf16 v[110:113], v[66:69], v[222:225], v[110:113]
	v_mfma_f32_16x16x32_bf16 v[106:109], v[74:77], v[222:225], v[106:109]
	v_mfma_f32_16x16x32_bf16 v[138:141], v[78:81], v[218:221], v[134:137]
	v_mfma_f32_16x16x32_bf16 v[110:113], v[70:73], v[226:229], v[110:113]
	v_mfma_f32_16x16x32_bf16 v[106:109], v[78:81], v[226:229], v[106:109]
	v_mfma_f32_16x16x32_bf16 v[82:85], v[238:241], v[118:121], v[82:85]
	v_mfma_f32_16x16x32_bf16 v[162:165], v[242:245], v[122:125], v[82:85]
	v_mfma_f32_16x16x32_bf16 v[82:85], v[230:233], v[126:129], v[86:89]
	v_mfma_f32_16x16x32_bf16 v[150:153], v[234:237], v[130:133], v[82:85]
	v_mfma_f32_16x16x32_bf16 v[82:85], v[238:241], v[126:129], v[94:97]
	v_mfma_f32_16x16x32_bf16 v[134:137], v[230:233], v[118:121], v[166:169]
	v_mfma_f32_16x16x32_bf16 v[146:149], v[242:245], v[130:133], v[82:85]
	v_mfma_f32_16x16x32_bf16 v[82:85], v[230:233], v[206:209], v[98:101]
	v_mfma_f32_16x16x32_bf16 v[166:169], v[234:237], v[122:125], v[134:137]
	v_mfma_f32_16x16x32_bf16 v[134:137], v[234:237], v[218:221], v[82:85]
	v_mfma_f32_16x16x32_bf16 v[82:85], v[238:241], v[206:209], v[114:117]
	v_mfma_f32_16x16x32_bf16 v[130:133], v[242:245], v[218:221], v[82:85]
	v_mfma_f32_16x16x32_bf16 v[82:85], v[230:233], v[222:225], v[102:105]
	v_mfma_f32_16x16x32_bf16 v[102:105], v[234:237], v[226:229], v[82:85]
	v_mfma_f32_16x16x32_bf16 v[82:85], v[238:241], v[222:225], v[90:93]
	v_mfma_f32_16x16x32_bf16 v[90:93], v[242:245], v[226:229], v[82:85]
	s_mov_b32 m0, s36
	v_lshl_add_u64 v[206:207], v[250:251], 0, s[70:71]
	s_barrier
; #define PG8_STAGE(bufoff, gbase, voff) do { _Pragma("unroll") for (int _i = 0; _i < 2; ++_i) \
;     __builtin_amdgcn_global_load_lds((const unsigned*)((const char*)(gbase) + (voff)[_i]), (LAS unsigned*)(lds + (bufoff) + ldsw + _i * 8192), 16, 0, 0); } while (0)
; #define PG8_LDA(dst, b, h) do { _Pragma("unroll") for (int m = 0; m < 4; ++m) _Pragma("unroll") for (int k = 0; k < 2; ++k) dst[m][k] = *(const LAS bf16x8*)(lds + PG8_SA(b, h) + aoff + m * 2048 + k * 1024); } while (0)
; #define PG8_MMA(ai, bj, At, Bt) do { __builtin_amdgcn_s_setprio(1); _Pragma("unroll") for (int m = 0; m < 4; ++m) _Pragma("unroll") for (int n = 0; n < 2; ++n) _Pragma("unroll") for (int k = 0; k < 2; ++k) \
;     acc[ai][bj][m][n] = __builtin_amdgcn_mfma_f32_16x16x32_bf16(Bt[n][k], At[m][k], acc[ai][bj][m][n], 0, 0, 0); __builtin_amdgcn_s_setprio(0); } while (0)
; #define PG8_WAIT_V(n) asm volatile("s_waitcnt vmcnt(" #n ")" ::: "memory")
; #define PG8_WAIT_L(n) asm volatile("s_waitcnt lgkmcnt(" #n ")" ::: "memory")
; #define PG8_BAR __builtin_amdgcn_s_barrier()
; #define PG8_SCHED __builtin_amdgcn_sched_barrier(0)
; template <class Epi, class Sched>
; DI void gemm_phase(LAS unsigned char* lds, const Gemm g, const Sched& S, const Epi& E) {
;     ...
;       PG8_LDA(At, 1, 1); PG8_STAGE(PG8_SA(1, 0), a3, voffA);
;       PG8_BAR; PG8_WAIT_L(0); PG8_MMA(1, 0, At, B0); PG8_BAR; PG8_SCHED;
;       PG8_STAGE(PG8_SB(1, 1), b3 + hstepB, voffB);
;       PG8_WAIT_V(6); PG8_BAR; PG8_MMA(1, 1, At, B1); PG8_BAR;
	s_nop 2
	ds_read_b128 v[82:85], v216 offset:49152
	ds_read_b128 v[86:89], v216 offset:50176
	ds_read_b128 v[94:97], v216 offset:51200
	ds_read_b128 v[98:101], v216 offset:52224
	ds_read_b128 v[114:117], v216 offset:53248
	ds_read_b128 v[118:121], v216 offset:54272
	ds_read_b128 v[122:125], v216 offset:55296
	ds_read_b128 v[126:129], v216 offset:56320
	global_load_lds_dwordx4 v[206:207], off
	v_lshl_add_u64 v[180:181], v[180:181], 0, s[70:71]
	s_mov_b32 m0, s37
	s_nop 0
	global_load_lds_dwordx4 v[180:181], off
	v_lshl_add_u64 v[246:247], v[246:247], 0, s[70:71]
	s_mov_b32 m0, s7
	s_nop 0
	global_load_lds_dwordx4 v[246:247], off
	v_lshl_add_u64 v[248:249], v[248:249], 0, s[70:71]
	s_add_i32 m0, s7, 0x2000
	s_nop 0
	global_load_lds_dwordx4 v[248:249], off
	s_add_i32 s6, s6, s29
	v_lshl_add_u64 v[246:247], v[182:183], 0, s[70:71]
	s_mov_b32 m0, s6
	s_nop 0
	global_load_lds_dwordx4 v[246:247], off
	v_lshl_add_u64 v[246:247], v[184:185], 0, s[70:71]
	s_add_i32 m0, s6, 0x2000
	s_nop 0
	global_load_lds_dwordx4 v[246:247], off
	s_waitcnt vmcnt(6)
	s_waitcnt lgkmcnt(0)
	s_barrier
	v_mfma_f32_16x16x32_bf16 v[62:65], v[66:69], v[82:85], v[62:65]
	v_mfma_f32_16x16x32_bf16 v[58:61], v[74:77], v[82:85], v[58:61]
	v_mfma_f32_16x16x32_bf16 v[46:49], v[66:69], v[94:97], v[46:49]
	v_mfma_f32_16x16x32_bf16 v[42:45], v[74:77], v[94:97], v[42:45]
	v_mfma_f32_16x16x32_bf16 v[30:33], v[66:69], v[114:117], v[30:33]
	v_mfma_f32_16x16x32_bf16 v[26:29], v[74:77], v[114:117], v[26:29]
	v_mfma_f32_16x16x32_bf16 v[14:17], v[66:69], v[122:125], v[14:17]
	v_mfma_f32_16x16x32_bf16 v[10:13], v[74:77], v[122:125], v[10:13]
	v_mfma_f32_16x16x32_bf16 v[62:65], v[70:73], v[86:89], v[62:65]
	v_mfma_f32_16x16x32_bf16 v[58:61], v[78:81], v[86:89], v[58:61]
	v_mfma_f32_16x16x32_bf16 v[46:49], v[70:73], v[98:101], v[46:49]
	v_mfma_f32_16x16x32_bf16 v[42:45], v[78:81], v[98:101], v[42:45]
	v_mfma_f32_16x16x32_bf16 v[30:33], v[70:73], v[118:121], v[30:33]
	v_mfma_f32_16x16x32_bf16 v[26:29], v[78:81], v[118:121], v[26:29]
	v_mfma_f32_16x16x32_bf16 v[14:17], v[70:73], v[126:129], v[14:17]
	v_mfma_f32_16x16x32_bf16 v[10:13], v[78:81], v[126:129], v[10:13]
	v_mfma_f32_16x16x32_bf16 v[54:57], v[230:233], v[82:85], v[54:57]
	v_mfma_f32_16x16x32_bf16 v[50:53], v[238:241], v[82:85], v[50:53]
	v_mfma_f32_16x16x32_bf16 v[38:41], v[230:233], v[94:97], v[38:41]
	v_mfma_f32_16x16x32_bf16 v[34:37], v[238:241], v[94:97], v[34:37]
	v_mfma_f32_16x16x32_bf16 v[22:25], v[230:233], v[114:117], v[22:25]
	v_mfma_f32_16x16x32_bf16 v[18:21], v[238:241], v[114:117], v[18:21]
	v_mfma_f32_16x16x32_bf16 v[6:9], v[230:233], v[122:125], v[6:9]
	v_mfma_f32_16x16x32_bf16 v[2:5], v[238:241], v[122:125], v[2:5]
	v_mfma_f32_16x16x32_bf16 v[54:57], v[234:237], v[86:89], v[54:57]
	v_mfma_f32_16x16x32_bf16 v[50:53], v[242:245], v[86:89], v[50:53]
	v_mfma_f32_16x16x32_bf16 v[38:41], v[234:237], v[98:101], v[38:41]
	v_mfma_f32_16x16x32_bf16 v[34:37], v[242:245], v[98:101], v[34:37]
	v_mfma_f32_16x16x32_bf16 v[22:25], v[234:237], v[118:121], v[22:25]
	v_mfma_f32_16x16x32_bf16 v[18:21], v[242:245], v[118:121], v[18:21]
	v_mfma_f32_16x16x32_bf16 v[6:9], v[234:237], v[126:129], v[6:9]
	v_mfma_f32_16x16x32_bf16 v[2:5], v[242:245], v[126:129], v[2:5]
	s_add_u32 s2, s2, 0x100
	s_addc_u32 s3, s3, 0
	s_add_u32 s11, s11, 0x100
	s_addc_u32 s22, s22, 0
	s_cmp_ge_i32 s23, s39
	s_mov_b32 s6, s23
	s_barrier
	s_cbranch_scc0 .LBB0_519
	v_mov_b64_e32 v[244:245], v[178:179]
	v_mov_b64_e32 v[178:179], 0xff
	v_mov_b64_e32 v[246:247], 0x1ff
	v_mov_b32_e32 v195, v217
	v_mov_b32_e32 v248, v210
	v_mov_b32_e32 v210, v201
	v_mov_b32_e32 v184, v200
